# PL2: pool items with wave-uniform window width (8 rows x 8 column blocks per wave, width classes paired per SIMD), only in-window taps loaded and accumulated with packed fma, same accumulation order
# baseline (speedup 1.0000x reference)
; __device__ __forceinline__ int otid() { int t = threadIdx.x; asm volatile("" : "+v"(t)); return t; }
; #define GAS __attribute__((address_space(1)))
; __device__ void pool_item(const Params& p, int item) {
;     const int tid = otid();
;     const int row = item * 16 + (tid >> 5), co = tid & 31, w = 2 << (co >> 3);
;     int base, T;
;     if (row < NL) { base = row & ~4095; T = 4096; } else { base = NL + ((row - NL) & ~255); T = 256; }
;     const int tt = row - base;
;     int lo = tt - (w >> 1), hi = lo + w; lo = lo < 0 ? 0 : lo; hi = hi > T ? T : hi;
;     const bf16_t* U = (const bf16_t*)(p.ws + OFF_P1) + 768 + 8 * co;
;     float s[8];
; #pragma unroll
;     for (int q = 0; q < 8; ++q) s[q] = 0.f;
;     const int wlo = tt - (w >> 1);
;     {
;         GAS const bf16_t* Ug = (GAS const bf16_t*)(unsigned long long)U;
;         u32x4 pv[16];
; #pragma unroll
;         for (int jj = 0; jj < 16; ++jj) { int j = wlo + jj; j = j < 0 ? 0 : (j >= T ? T - 1 : j); pv[jj] = *(GAS const u32x4*)(Ug + (size_t)(base + j) * P1LD); }
;         asm volatile("" ::: "memory");
.LBB0_37:
	s_cmp_ge_i32 s29, s10
	s_mov_b64 s[4:5], -1
	s_cbranch_scc0 .LBB0_66
	s_cmp_ge_i32 s29, s12
	s_cbranch_scc0 .LBB0_40
	v_mov_b32_e32 v0, v210
	s_add_i32 s2, s29, s13
	v_lshrrev_b32_e32 v1, 6, v0
	s_nop 0
	v_readfirstlane_b32 s40, v1
	s_sub_i32 s41, 7, s40
	s_cmp_lt_u32 s40, 4
	s_cselect_b32 s41, s40, s41
	s_lshr_b32 s42, s40, 2
	s_lshl_b32 s43, 2, s41
	s_lshl_b32 s44, s2, 4
	s_lshl_b32 s45, s42, 3
	s_add_i32 s44, s44, s45
	v_bfe_u32 v1, v0, 3, 3
	v_add_u32_e32 v42, s44, v1
	v_and_b32_e32 v80, 7, v0
	v_lshl_add_u32 v80, s41, 3, v80
	v_mov_b32_e32 v81, s41
	v_mov_b32_e32 v43, s43
	v_mov_b32_e32 v2, 0x1000
	v_cmp_gt_i32_e32 vcc, s75, v42
	v_mov_b32_e32 v0, 0x7fffff00
	v_mov_b32_e32 v1, 0xfffff000
	s_nop 0
	v_cndmask_b32_e32 v0, v0, v1, vcc
	v_and_b32_e32 v4, v0, v42
	v_lshrrev_b32_e32 v0, 1, v43
	v_mov_b32_e32 v1, 0x100
	v_or_b32_e32 v0, v4, v0
	v_cndmask_b32_e32 v44, v1, v2, vcc
	v_sub_u32_e32 v45, v42, v0
	v_add_u32_e32 v5, -1, v44
	v_lshlrev_b32_e32 v96, 4, v80
	v_lshl_add_u64 v[40:41], v[134:135], 0, v[96:97]
	v_mad_i64_i32 v[8:9], s[4:5], v42, s38, v[40:41]
	global_load_dwordx4 v[12:15], v[8:9], off
	v_add_u32_e32 v6, 0, v45
	v_med3_i32 v6, v6, 0, v5
	v_add_u32_e32 v6, v6, v4
	v_mad_i64_i32 v[0:1], s[4:5], v6, s38, v[40:41]
	global_load_dwordx4 v[140:143], v[0:1], off
	v_add_u32_e32 v7, 1, v45
	v_med3_i32 v7, v7, 0, v5
	v_add_u32_e32 v7, v7, v4
	v_mad_i64_i32 v[2:3], s[4:5], v7, s38, v[40:41]
	global_load_dwordx4 v[144:147], v[2:3], off
	s_cmp_lt_u32 s43, 4
	s_cbranch_scc1 .Lmy_pl_ld
	v_add_u32_e32 v6, 2, v45
	v_med3_i32 v6, v6, 0, v5
	v_add_u32_e32 v6, v6, v4
	v_mad_i64_i32 v[0:1], s[4:5], v6, s38, v[40:41]
	global_load_dwordx4 v[148:151], v[0:1], off
	v_add_u32_e32 v7, 3, v45
	v_med3_i32 v7, v7, 0, v5
	v_add_u32_e32 v7, v7, v4
	v_mad_i64_i32 v[2:3], s[4:5], v7, s38, v[40:41]
	global_load_dwordx4 v[152:155], v[2:3], off
	s_cmp_lt_u32 s43, 8
	s_cbranch_scc1 .Lmy_pl_ld
	v_add_u32_e32 v6, 4, v45
	v_med3_i32 v6, v6, 0, v5
	v_add_u32_e32 v6, v6, v4
	v_mad_i64_i32 v[0:1], s[4:5], v6, s38, v[40:41]
	global_load_dwordx4 v[156:159], v[0:1], off
	v_add_u32_e32 v7, 5, v45
	v_med3_i32 v7, v7, 0, v5
	v_add_u32_e32 v7, v7, v4
	v_mad_i64_i32 v[2:3], s[4:5], v7, s38, v[40:41]
	global_load_dwordx4 v[160:163], v[2:3], off
	v_add_u32_e32 v6, 6, v45
	v_med3_i32 v6, v6, 0, v5
	v_add_u32_e32 v6, v6, v4
	v_mad_i64_i32 v[0:1], s[4:5], v6, s38, v[40:41]
	global_load_dwordx4 v[164:167], v[0:1], off
	v_add_u32_e32 v7, 7, v45
	v_med3_i32 v7, v7, 0, v5
	v_add_u32_e32 v7, v7, v4
	v_mad_i64_i32 v[2:3], s[4:5], v7, s38, v[40:41]
	global_load_dwordx4 v[168:171], v[2:3], off
	s_cmp_lt_u32 s43, 16
	s_cbranch_scc1 .Lmy_pl_ld
	v_add_u32_e32 v6, 8, v45
	v_med3_i32 v6, v6, 0, v5
	v_add_u32_e32 v6, v6, v4
	v_mad_i64_i32 v[0:1], s[4:5], v6, s38, v[40:41]
	global_load_dwordx4 v[172:175], v[0:1], off
	v_add_u32_e32 v7, 9, v45
	v_med3_i32 v7, v7, 0, v5
	v_add_u32_e32 v7, v7, v4
	v_mad_i64_i32 v[2:3], s[4:5], v7, s38, v[40:41]
	global_load_dwordx4 v[176:179], v[2:3], off
	v_add_u32_e32 v6, 10, v45
	v_med3_i32 v6, v6, 0, v5
	v_add_u32_e32 v6, v6, v4
	v_mad_i64_i32 v[0:1], s[4:5], v6, s38, v[40:41]
	global_load_dwordx4 v[180:183], v[0:1], off
	v_add_u32_e32 v7, 11, v45
	v_med3_i32 v7, v7, 0, v5
	v_add_u32_e32 v7, v7, v4
	v_mad_i64_i32 v[2:3], s[4:5], v7, s38, v[40:41]
	global_load_dwordx4 v[184:187], v[2:3], off
	v_add_u32_e32 v6, 12, v45
	v_med3_i32 v6, v6, 0, v5
	v_add_u32_e32 v6, v6, v4
	v_mad_i64_i32 v[0:1], s[4:5], v6, s38, v[40:41]
	global_load_dwordx4 v[188:191], v[0:1], off
	v_add_u32_e32 v7, 13, v45
	v_med3_i32 v7, v7, 0, v5
	v_add_u32_e32 v7, v7, v4
	v_mad_i64_i32 v[2:3], s[4:5], v7, s38, v[40:41]
	global_load_dwordx4 v[192:195], v[2:3], off
	v_add_u32_e32 v6, 14, v45
	v_med3_i32 v6, v6, 0, v5
	v_add_u32_e32 v6, v6, v4
	v_mad_i64_i32 v[0:1], s[4:5], v6, s38, v[40:41]
	global_load_dwordx4 v[196:199], v[0:1], off
	v_add_u32_e32 v7, 15, v45
	v_med3_i32 v7, v7, 0, v5
	v_add_u32_e32 v7, v7, v4
	v_mad_i64_i32 v[2:3], s[4:5], v7, s38, v[40:41]
	global_load_dwordx4 v[200:203], v[2:3], off
.Lmy_pl_ld:
	v_add_u32_e32 v6, 0, v45
	v_cmp_lt_u32_e64 s[46:47], v6, v44
	s_nop 1
	v_cndmask_b32_e64 v100, 0, 1.0, s[46:47]
	v_add_u32_e32 v6, 1, v45
	v_cmp_lt_u32_e64 s[50:51], v6, v44
	s_nop 1
	v_cndmask_b32_e64 v102, 0, 1.0, s[50:51]
	s_cmp_lt_u32 s43, 4
	s_cbranch_scc1 .Lmy_pl_mk
	v_add_u32_e32 v6, 2, v45
	v_cmp_lt_u32_e64 s[46:47], v6, v44
	s_nop 1
	v_cndmask_b32_e64 v104, 0, 1.0, s[46:47]
	v_add_u32_e32 v6, 3, v45
	v_cmp_lt_u32_e64 s[50:51], v6, v44
	s_nop 1
	v_cndmask_b32_e64 v106, 0, 1.0, s[50:51]
	s_cmp_lt_u32 s43, 8
	s_cbranch_scc1 .Lmy_pl_mk
	v_add_u32_e32 v6, 4, v45
	v_cmp_lt_u32_e64 s[46:47], v6, v44
	s_nop 1
	v_cndmask_b32_e64 v108, 0, 1.0, s[46:47]
	v_add_u32_e32 v6, 5, v45
	v_cmp_lt_u32_e64 s[50:51], v6, v44
	s_nop 1
	v_cndmask_b32_e64 v110, 0, 1.0, s[50:51]
	v_add_u32_e32 v6, 6, v45
	v_cmp_lt_u32_e64 s[46:47], v6, v44
	s_nop 1
	v_cndmask_b32_e64 v112, 0, 1.0, s[46:47]
	v_add_u32_e32 v6, 7, v45
	v_cmp_lt_u32_e64 s[50:51], v6, v44
	s_nop 1
	v_cndmask_b32_e64 v114, 0, 1.0, s[50:51]
	s_cmp_lt_u32 s43, 16
	s_cbranch_scc1 .Lmy_pl_mk
	v_add_u32_e32 v6, 8, v45
	v_cmp_lt_u32_e64 s[46:47], v6, v44
	s_nop 1
	v_cndmask_b32_e64 v116, 0, 1.0, s[46:47]
	v_add_u32_e32 v6, 9, v45
	v_cmp_lt_u32_e64 s[50:51], v6, v44
	s_nop 1
	v_cndmask_b32_e64 v118, 0, 1.0, s[50:51]
	v_add_u32_e32 v6, 10, v45
	v_cmp_lt_u32_e64 s[46:47], v6, v44
	s_nop 1
	v_cndmask_b32_e64 v120, 0, 1.0, s[46:47]
	v_add_u32_e32 v6, 11, v45
	v_cmp_lt_u32_e64 s[50:51], v6, v44
	s_nop 1
	v_cndmask_b32_e64 v122, 0, 1.0, s[50:51]
	v_add_u32_e32 v6, 12, v45
	v_cmp_lt_u32_e64 s[46:47], v6, v44
	s_nop 1
	v_cndmask_b32_e64 v124, 0, 1.0, s[46:47]
	v_add_u32_e32 v6, 13, v45
	v_cmp_lt_u32_e64 s[50:51], v6, v44
	s_nop 1
	v_cndmask_b32_e64 v126, 0, 1.0, s[50:51]
	v_add_u32_e32 v6, 14, v45
	v_cmp_lt_u32_e64 s[46:47], v6, v44
	s_nop 1
	v_cndmask_b32_e64 v128, 0, 1.0, s[46:47]
	v_add_u32_e32 v6, 15, v45
	v_cmp_lt_u32_e64 s[50:51], v6, v44
	s_nop 1
	v_cndmask_b32_e64 v130, 0, 1.0, s[50:51]
; __device__ __forceinline__ float bflo(unsigned w) { return __uint_as_float(w << 16); }
; __device__ __forceinline__ float bfhi(unsigned w) { return __uint_as_float(w & 0xffff0000u); }
; #define GAS __attribute__((address_space(1)))
; __device__ void pool_item(const Params& p, int item) {
;     ...
;     const int wlo = tt - (w >> 1);
;     {
;         GAS const bf16_t* Ug = (GAS const bf16_t*)(unsigned long long)U;
;         u32x4 pv[16];
; #pragma unroll
;         for (int jj = 0; jj < 16; ++jj) { int j = wlo + jj; j = j < 0 ? 0 : (j >= T ? T - 1 : j); pv[jj] = *(GAS const u32x4*)(Ug + (size_t)(base + j) * P1LD); }
;         asm volatile("" ::: "memory");
; #pragma unroll
;         for (int jj = 0; jj < 16; ++jj) {
;             const int j = wlo + jj; const float mk = (jj < w && j >= 0 && j < T) ? 1.f : 0.f; const u32x4 v = pv[jj];
;             s[0] += mk * bflo(v.x); s[1] += mk * bfhi(v.x); s[2] += mk * bflo(v.y); s[3] += mk * bfhi(v.y); s[4] += mk * bflo(v.z); s[5] += mk * bfhi(v.z); s[6] += mk * bflo(v.w); s[7] += mk * bfhi(v.w);
;         }
;     }
;     const float ic = 1.f / (float)(hi - lo);
.Lmy_pl_mk:
	v_add_u32_e32 v17, v45, v43
	v_min_i32_e32 v17, v17, v44
	v_max_i32_e32 v18, 0, v45
	v_sub_u32_e32 v17, v17, v18
	v_cvt_f32_i32_e32 v17, v17
	v_div_scale_f32 v18, s[4:5], v17, v17, 1.0
	v_rcp_f32_e32 v21, v18
	s_nop 0
	v_fma_f32 v16, -v18, v21, 1.0
	v_fmac_f32_e32 v21, v16, v21
	v_div_scale_f32 v16, vcc, 1.0, v17, 1.0
	v_mul_f32_e32 v19, v16, v21
	v_fma_f32 v20, -v18, v19, v16
	v_fmac_f32_e32 v19, v20, v21
	v_fma_f32 v16, -v18, v19, v16
	s_nop 1
	v_div_fmas_f32 v16, v16, v21, v19
	v_div_fixup_f32 v19, v16, v17, 1.0
	v_mov_b32_e32 v46, 0
	v_mov_b32_e32 v47, 0
	v_mov_b32_e32 v48, 0
	v_mov_b32_e32 v49, 0
	v_mov_b32_e32 v50, 0
	v_mov_b32_e32 v51, 0
	v_mov_b32_e32 v52, 0
	v_mov_b32_e32 v53, 0
	s_waitcnt vmcnt(0)
	v_lshlrev_b32_e32 v6, 16, v140
	v_and_b32_e32 v7, 0xffff0000, v140
	v_pk_fma_f32 v[52:53], v[100:101], v[6:7], v[52:53] op_sel_hi:[0,1,1]
	v_lshlrev_b32_e32 v8, 16, v141
	v_and_b32_e32 v9, 0xffff0000, v141
	v_pk_fma_f32 v[50:51], v[100:101], v[8:9], v[50:51] op_sel_hi:[0,1,1]
	v_lshlrev_b32_e32 v10, 16, v142
	v_and_b32_e32 v11, 0xffff0000, v142
	v_pk_fma_f32 v[48:49], v[100:101], v[10:11], v[48:49] op_sel_hi:[0,1,1]
	v_lshlrev_b32_e32 v22, 16, v143
	v_and_b32_e32 v23, 0xffff0000, v143
	v_pk_fma_f32 v[46:47], v[100:101], v[22:23], v[46:47] op_sel_hi:[0,1,1]
	v_lshlrev_b32_e32 v6, 16, v144
	v_and_b32_e32 v7, 0xffff0000, v144
	v_pk_fma_f32 v[52:53], v[102:103], v[6:7], v[52:53] op_sel_hi:[0,1,1]
	v_lshlrev_b32_e32 v8, 16, v145
	v_and_b32_e32 v9, 0xffff0000, v145
	v_pk_fma_f32 v[50:51], v[102:103], v[8:9], v[50:51] op_sel_hi:[0,1,1]
	v_lshlrev_b32_e32 v10, 16, v146
	v_and_b32_e32 v11, 0xffff0000, v146
	v_pk_fma_f32 v[48:49], v[102:103], v[10:11], v[48:49] op_sel_hi:[0,1,1]
	v_lshlrev_b32_e32 v22, 16, v147
	v_and_b32_e32 v23, 0xffff0000, v147
	v_pk_fma_f32 v[46:47], v[102:103], v[22:23], v[46:47] op_sel_hi:[0,1,1]
	s_cmp_lt_u32 s43, 4
	s_cbranch_scc1 .Lmy_pl_acc
	v_lshlrev_b32_e32 v6, 16, v148
	v_and_b32_e32 v7, 0xffff0000, v148
	v_pk_fma_f32 v[52:53], v[104:105], v[6:7], v[52:53] op_sel_hi:[0,1,1]
	v_lshlrev_b32_e32 v8, 16, v149
	v_and_b32_e32 v9, 0xffff0000, v149
	v_pk_fma_f32 v[50:51], v[104:105], v[8:9], v[50:51] op_sel_hi:[0,1,1]
	v_lshlrev_b32_e32 v10, 16, v150
	v_and_b32_e32 v11, 0xffff0000, v150
	v_pk_fma_f32 v[48:49], v[104:105], v[10:11], v[48:49] op_sel_hi:[0,1,1]
	v_lshlrev_b32_e32 v22, 16, v151
	v_and_b32_e32 v23, 0xffff0000, v151
	v_pk_fma_f32 v[46:47], v[104:105], v[22:23], v[46:47] op_sel_hi:[0,1,1]
	v_lshlrev_b32_e32 v6, 16, v152
	v_and_b32_e32 v7, 0xffff0000, v152
	v_pk_fma_f32 v[52:53], v[106:107], v[6:7], v[52:53] op_sel_hi:[0,1,1]
	v_lshlrev_b32_e32 v8, 16, v153
	v_and_b32_e32 v9, 0xffff0000, v153
	v_pk_fma_f32 v[50:51], v[106:107], v[8:9], v[50:51] op_sel_hi:[0,1,1]
	v_lshlrev_b32_e32 v10, 16, v154
	v_and_b32_e32 v11, 0xffff0000, v154
	v_pk_fma_f32 v[48:49], v[106:107], v[10:11], v[48:49] op_sel_hi:[0,1,1]
	v_lshlrev_b32_e32 v22, 16, v155
	v_and_b32_e32 v23, 0xffff0000, v155
	v_pk_fma_f32 v[46:47], v[106:107], v[22:23], v[46:47] op_sel_hi:[0,1,1]
	s_cmp_lt_u32 s43, 8
	s_cbranch_scc1 .Lmy_pl_acc
	v_lshlrev_b32_e32 v6, 16, v156
	v_and_b32_e32 v7, 0xffff0000, v156
	v_pk_fma_f32 v[52:53], v[108:109], v[6:7], v[52:53] op_sel_hi:[0,1,1]
	v_lshlrev_b32_e32 v8, 16, v157
	v_and_b32_e32 v9, 0xffff0000, v157
	v_pk_fma_f32 v[50:51], v[108:109], v[8:9], v[50:51] op_sel_hi:[0,1,1]
	v_lshlrev_b32_e32 v10, 16, v158
	v_and_b32_e32 v11, 0xffff0000, v158
	v_pk_fma_f32 v[48:49], v[108:109], v[10:11], v[48:49] op_sel_hi:[0,1,1]
	v_lshlrev_b32_e32 v22, 16, v159
	v_and_b32_e32 v23, 0xffff0000, v159
	v_pk_fma_f32 v[46:47], v[108:109], v[22:23], v[46:47] op_sel_hi:[0,1,1]
	v_lshlrev_b32_e32 v6, 16, v160
	v_and_b32_e32 v7, 0xffff0000, v160
	v_pk_fma_f32 v[52:53], v[110:111], v[6:7], v[52:53] op_sel_hi:[0,1,1]
	v_lshlrev_b32_e32 v8, 16, v161
	v_and_b32_e32 v9, 0xffff0000, v161
	v_pk_fma_f32 v[50:51], v[110:111], v[8:9], v[50:51] op_sel_hi:[0,1,1]
	v_lshlrev_b32_e32 v10, 16, v162
	v_and_b32_e32 v11, 0xffff0000, v162
	v_pk_fma_f32 v[48:49], v[110:111], v[10:11], v[48:49] op_sel_hi:[0,1,1]
	v_lshlrev_b32_e32 v22, 16, v163
	v_and_b32_e32 v23, 0xffff0000, v163
	v_pk_fma_f32 v[46:47], v[110:111], v[22:23], v[46:47] op_sel_hi:[0,1,1]
	v_lshlrev_b32_e32 v6, 16, v164
	v_and_b32_e32 v7, 0xffff0000, v164
	v_pk_fma_f32 v[52:53], v[112:113], v[6:7], v[52:53] op_sel_hi:[0,1,1]
	v_lshlrev_b32_e32 v8, 16, v165
	v_and_b32_e32 v9, 0xffff0000, v165
	v_pk_fma_f32 v[50:51], v[112:113], v[8:9], v[50:51] op_sel_hi:[0,1,1]
	v_lshlrev_b32_e32 v10, 16, v166
	v_and_b32_e32 v11, 0xffff0000, v166
	v_pk_fma_f32 v[48:49], v[112:113], v[10:11], v[48:49] op_sel_hi:[0,1,1]
	v_lshlrev_b32_e32 v22, 16, v167
	v_and_b32_e32 v23, 0xffff0000, v167
	v_pk_fma_f32 v[46:47], v[112:113], v[22:23], v[46:47] op_sel_hi:[0,1,1]
	v_lshlrev_b32_e32 v6, 16, v168
	v_and_b32_e32 v7, 0xffff0000, v168
	v_pk_fma_f32 v[52:53], v[114:115], v[6:7], v[52:53] op_sel_hi:[0,1,1]
	v_lshlrev_b32_e32 v8, 16, v169
	v_and_b32_e32 v9, 0xffff0000, v169
	v_pk_fma_f32 v[50:51], v[114:115], v[8:9], v[50:51] op_sel_hi:[0,1,1]
	v_lshlrev_b32_e32 v10, 16, v170
	v_and_b32_e32 v11, 0xffff0000, v170
	v_pk_fma_f32 v[48:49], v[114:115], v[10:11], v[48:49] op_sel_hi:[0,1,1]
	v_lshlrev_b32_e32 v22, 16, v171
	v_and_b32_e32 v23, 0xffff0000, v171
	v_pk_fma_f32 v[46:47], v[114:115], v[22:23], v[46:47] op_sel_hi:[0,1,1]
	s_cmp_lt_u32 s43, 16
	s_cbranch_scc1 .Lmy_pl_acc
; __device__ __forceinline__ unsigned pk2(float lo, float hi) { unsigned r; asm volatile("v_cvt_pk_bf16_f32 %0, %1, %2" : "=v"(r) : "v"(lo), "v"(hi)); return r; }
; __device__ __forceinline__ float bflo(unsigned w) { return __uint_as_float(w << 16); }
; __device__ __forceinline__ float bfhi(unsigned w) { return __uint_as_float(w & 0xffff0000u); }
; __device__ void pool_item(const Params& p, int item) {
;     ...
; #pragma unroll
;         for (int jj = 0; jj < 16; ++jj) {
;             const int j = wlo + jj; const float mk = (jj < w && j >= 0 && j < T) ? 1.f : 0.f; const u32x4 v = pv[jj];
;             s[0] += mk * bflo(v.x); s[1] += mk * bfhi(v.x); s[2] += mk * bflo(v.y); s[3] += mk * bfhi(v.y); s[4] += mk * bflo(v.z); s[5] += mk * bfhi(v.z); s[6] += mk * bflo(v.w); s[7] += mk * bfhi(v.w);
;         }
;     }
;     const float ic = 1.f / (float)(hi - lo);
;     const u32x4 v = *(const u32x4*)(U + (size_t)row * P1LD);
;     u32x4 o; o.x = pk2(s[0] * ic - bflo(v.x), s[1] * ic - bfhi(v.x)); o.y = pk2(s[2] * ic - bflo(v.y), s[3] * ic - bfhi(v.y));
;     o.z = pk2(s[4] * ic - bflo(v.z), s[5] * ic - bfhi(v.z)); o.w = pk2(s[6] * ic - bflo(v.w), s[7] * ic - bfhi(v.w));
;     *(u32x4*)((bf16_t*)(p.ws + OFF_AM) + (size_t)row * 1280 + 512 + 8 * co) = o;
	v_lshlrev_b32_e32 v6, 16, v172
	v_and_b32_e32 v7, 0xffff0000, v172
	v_pk_fma_f32 v[52:53], v[116:117], v[6:7], v[52:53] op_sel_hi:[0,1,1]
	v_lshlrev_b32_e32 v8, 16, v173
	v_and_b32_e32 v9, 0xffff0000, v173
	v_pk_fma_f32 v[50:51], v[116:117], v[8:9], v[50:51] op_sel_hi:[0,1,1]
	v_lshlrev_b32_e32 v10, 16, v174
	v_and_b32_e32 v11, 0xffff0000, v174
	v_pk_fma_f32 v[48:49], v[116:117], v[10:11], v[48:49] op_sel_hi:[0,1,1]
	v_lshlrev_b32_e32 v22, 16, v175
	v_and_b32_e32 v23, 0xffff0000, v175
	v_pk_fma_f32 v[46:47], v[116:117], v[22:23], v[46:47] op_sel_hi:[0,1,1]
	v_lshlrev_b32_e32 v6, 16, v176
	v_and_b32_e32 v7, 0xffff0000, v176
	v_pk_fma_f32 v[52:53], v[118:119], v[6:7], v[52:53] op_sel_hi:[0,1,1]
	v_lshlrev_b32_e32 v8, 16, v177
	v_and_b32_e32 v9, 0xffff0000, v177
	v_pk_fma_f32 v[50:51], v[118:119], v[8:9], v[50:51] op_sel_hi:[0,1,1]
	v_lshlrev_b32_e32 v10, 16, v178
	v_and_b32_e32 v11, 0xffff0000, v178
	v_pk_fma_f32 v[48:49], v[118:119], v[10:11], v[48:49] op_sel_hi:[0,1,1]
	v_lshlrev_b32_e32 v22, 16, v179
	v_and_b32_e32 v23, 0xffff0000, v179
	v_pk_fma_f32 v[46:47], v[118:119], v[22:23], v[46:47] op_sel_hi:[0,1,1]
	v_lshlrev_b32_e32 v6, 16, v180
	v_and_b32_e32 v7, 0xffff0000, v180
	v_pk_fma_f32 v[52:53], v[120:121], v[6:7], v[52:53] op_sel_hi:[0,1,1]
	v_lshlrev_b32_e32 v8, 16, v181
	v_and_b32_e32 v9, 0xffff0000, v181
	v_pk_fma_f32 v[50:51], v[120:121], v[8:9], v[50:51] op_sel_hi:[0,1,1]
	v_lshlrev_b32_e32 v10, 16, v182
	v_and_b32_e32 v11, 0xffff0000, v182
	v_pk_fma_f32 v[48:49], v[120:121], v[10:11], v[48:49] op_sel_hi:[0,1,1]
	v_lshlrev_b32_e32 v22, 16, v183
	v_and_b32_e32 v23, 0xffff0000, v183
	v_pk_fma_f32 v[46:47], v[120:121], v[22:23], v[46:47] op_sel_hi:[0,1,1]
	v_lshlrev_b32_e32 v6, 16, v184
	v_and_b32_e32 v7, 0xffff0000, v184
	v_pk_fma_f32 v[52:53], v[122:123], v[6:7], v[52:53] op_sel_hi:[0,1,1]
	v_lshlrev_b32_e32 v8, 16, v185
	v_and_b32_e32 v9, 0xffff0000, v185
	v_pk_fma_f32 v[50:51], v[122:123], v[8:9], v[50:51] op_sel_hi:[0,1,1]
	v_lshlrev_b32_e32 v10, 16, v186
	v_and_b32_e32 v11, 0xffff0000, v186
	v_pk_fma_f32 v[48:49], v[122:123], v[10:11], v[48:49] op_sel_hi:[0,1,1]
	v_lshlrev_b32_e32 v22, 16, v187
	v_and_b32_e32 v23, 0xffff0000, v187
	v_pk_fma_f32 v[46:47], v[122:123], v[22:23], v[46:47] op_sel_hi:[0,1,1]
	v_lshlrev_b32_e32 v6, 16, v188
	v_and_b32_e32 v7, 0xffff0000, v188
	v_pk_fma_f32 v[52:53], v[124:125], v[6:7], v[52:53] op_sel_hi:[0,1,1]
	v_lshlrev_b32_e32 v8, 16, v189
	v_and_b32_e32 v9, 0xffff0000, v189
	v_pk_fma_f32 v[50:51], v[124:125], v[8:9], v[50:51] op_sel_hi:[0,1,1]
	v_lshlrev_b32_e32 v10, 16, v190
	v_and_b32_e32 v11, 0xffff0000, v190
	v_pk_fma_f32 v[48:49], v[124:125], v[10:11], v[48:49] op_sel_hi:[0,1,1]
	v_lshlrev_b32_e32 v22, 16, v191
	v_and_b32_e32 v23, 0xffff0000, v191
	v_pk_fma_f32 v[46:47], v[124:125], v[22:23], v[46:47] op_sel_hi:[0,1,1]
	v_lshlrev_b32_e32 v6, 16, v192
	v_and_b32_e32 v7, 0xffff0000, v192
	v_pk_fma_f32 v[52:53], v[126:127], v[6:7], v[52:53] op_sel_hi:[0,1,1]
	v_lshlrev_b32_e32 v8, 16, v193
	v_and_b32_e32 v9, 0xffff0000, v193
	v_pk_fma_f32 v[50:51], v[126:127], v[8:9], v[50:51] op_sel_hi:[0,1,1]
	v_lshlrev_b32_e32 v10, 16, v194
	v_and_b32_e32 v11, 0xffff0000, v194
	v_pk_fma_f32 v[48:49], v[126:127], v[10:11], v[48:49] op_sel_hi:[0,1,1]
	v_lshlrev_b32_e32 v22, 16, v195
	v_and_b32_e32 v23, 0xffff0000, v195
	v_pk_fma_f32 v[46:47], v[126:127], v[22:23], v[46:47] op_sel_hi:[0,1,1]
	v_lshlrev_b32_e32 v6, 16, v196
	v_and_b32_e32 v7, 0xffff0000, v196
	v_pk_fma_f32 v[52:53], v[128:129], v[6:7], v[52:53] op_sel_hi:[0,1,1]
	v_lshlrev_b32_e32 v8, 16, v197
	v_and_b32_e32 v9, 0xffff0000, v197
	v_pk_fma_f32 v[50:51], v[128:129], v[8:9], v[50:51] op_sel_hi:[0,1,1]
	v_lshlrev_b32_e32 v10, 16, v198
	v_and_b32_e32 v11, 0xffff0000, v198
	v_pk_fma_f32 v[48:49], v[128:129], v[10:11], v[48:49] op_sel_hi:[0,1,1]
	v_lshlrev_b32_e32 v22, 16, v199
	v_and_b32_e32 v23, 0xffff0000, v199
	v_pk_fma_f32 v[46:47], v[128:129], v[22:23], v[46:47] op_sel_hi:[0,1,1]
	v_lshlrev_b32_e32 v6, 16, v200
	v_and_b32_e32 v7, 0xffff0000, v200
	v_pk_fma_f32 v[52:53], v[130:131], v[6:7], v[52:53] op_sel_hi:[0,1,1]
	v_lshlrev_b32_e32 v8, 16, v201
	v_and_b32_e32 v9, 0xffff0000, v201
	v_pk_fma_f32 v[50:51], v[130:131], v[8:9], v[50:51] op_sel_hi:[0,1,1]
	v_lshlrev_b32_e32 v10, 16, v202
	v_and_b32_e32 v11, 0xffff0000, v202
	v_pk_fma_f32 v[48:49], v[130:131], v[10:11], v[48:49] op_sel_hi:[0,1,1]
	v_lshlrev_b32_e32 v22, 16, v203
	v_and_b32_e32 v23, 0xffff0000, v203
	v_pk_fma_f32 v[46:47], v[130:131], v[22:23], v[46:47] op_sel_hi:[0,1,1]
.Lmy_pl_acc:
	v_lshlrev_b32_e32 v0, 16, v12
	v_and_b32_e32 v1, 0xffff0000, v12
	v_fma_f32 v0, v19, v52, -v0
	v_fma_f32 v1, v19, v53, -v1
	v_cvt_pk_bf16_f32 v0, v0, v1
	v_lshlrev_b32_e32 v1, 16, v13
	v_and_b32_e32 v2, 0xffff0000, v13
	v_fma_f32 v1, v19, v50, -v1
	v_fma_f32 v2, v19, v51, -v2
	v_cvt_pk_bf16_f32 v1, v1, v2
	v_lshlrev_b32_e32 v2, 16, v14
	v_and_b32_e32 v4, 0xffff0000, v14
	v_fma_f32 v2, v19, v48, -v2
	v_fma_f32 v4, v19, v49, -v4
	v_cvt_pk_bf16_f32 v2, v2, v4
	v_lshlrev_b32_e32 v4, 16, v15
	v_and_b32_e32 v5, 0xffff0000, v15
	v_fma_f32 v4, v19, v46, -v4
	v_fma_f32 v3, v19, v47, -v5
	v_cvt_pk_bf16_f32 v3, v4, v3
	v_mad_i64_i32 v[4:5], s[4:5], v42, s38, v[132:133]
	v_lshl_add_u64 v[4:5], v[4:5], 0, v[96:97]
	v_add_co_u32_e32 v4, vcc, 0x8d80000, v4
	v_readlane_b32 s60, v254, 57
	s_nop 0
	v_addc_co_u32_e32 v5, vcc, 0, v5, vcc
	v_readlane_b32 s61, v254, 58
	s_mov_b32 s59, 0x7f800000
	s_mov_b32 s58, 0x800000
	s_movk_i32 s62, 0x3fff
	s_movk_i32 s63, 0xff00
	s_mov_b32 s39, 0xffff0000
	s_movk_i32 s38, 0xa00
	s_movk_i32 s2, 0xa00
	s_mov_b64 s[54:55], 0x8d80600
	global_store_dwordx4 v[4:5], v[0:3], off offset:1024
	s_mov_b64 s[4:5], 0
